# v44 + packed f32 VALU ops in the two attention (MFMA+softmax) regions unpacked into scalar f32 pairs
# speedup vs baseline: 1.0063x; 1.0063x over previous
.LBB0_180:
	v_lshl_add_u64 v[40:41], v[142:143], 0, s[36:37]
	v_lshl_add_u64 v[42:43], v[144:145], 0, s[36:37]
	global_load_dwordx4 v[60:63], v[40:41], off
	global_load_dwordx4 v[56:59], v[42:43], off
	v_lshl_add_u64 v[40:41], v[146:147], 0, s[36:37]
	global_load_dwordx4 v[48:51], v[40:41], off
	global_load_dwordx4 v[44:47], v[150:151], off offset:-8
	s_nop 0
	global_load_dwordx4 v[40:43], v[148:149], off offset:-8
	s_and_b32 s53, s52, 1
	s_mul_i32 s40, s53, 0x5800
	v_or_b32_e32 v80, s40, v128
	v_add_u32_e32 v159, v80, v158
	ds_read_b128 v[92:95], v159
	ds_read_b128 v[96:99], v159 offset:64
	ds_read_b128 v[108:111], v159 offset:128
	ds_read_b128 v[112:115], v159 offset:3328
	s_waitcnt lgkmcnt(3)
	v_mfma_f32_16x16x32_bf16 v[76:79], v[92:95], v[20:23], 0
	ds_read_b128 v[104:107], v159 offset:3392
	ds_read_b128 v[100:103], v159 offset:3456
	v_add_u32_e32 v160, v80, v157
	s_waitcnt lgkmcnt(4)
	v_mfma_f32_16x16x32_bf16 v[76:79], v[96:99], v[12:15], v[76:79]
	s_mov_b32 s4, 0x41000000
	s_waitcnt lgkmcnt(3)
	v_mfma_f32_16x16x32_bf16 v[116:119], v[108:111], v[16:19], v[76:79]
	s_waitcnt lgkmcnt(2)
	v_mfma_f32_16x16x32_bf16 v[76:79], v[112:115], v[20:23], 0
	s_waitcnt lgkmcnt(1)
	v_mfma_f32_16x16x32_bf16 v[120:123], v[104:107], v[12:15], v[76:79]
	s_nop 3
	v_max_f32_e32 v161, v117, v117
	v_max_f32_e32 v162, v116, v116
	v_max_f32_e32 v161, v162, v161
	s_waitcnt lgkmcnt(0)
	v_mfma_f32_16x16x32_bf16 v[120:123], v[100:103], v[16:19], v[120:123]
	v_max_f32_e32 v162, v119, v119
	v_max_f32_e32 v163, v118, v118
	v_max_f32_e32 v162, v163, v162
	ds_read_b128 v[80:83], v160 offset:13312
	ds_read_b128 v[84:87], v160 offset:15616
	ds_read_b128 v[88:91], v160 offset:17920
	ds_read_b128 v[76:79], v160 offset:20224
	s_nop 0
	v_max_f32_e32 v163, v123, v123
	v_max_f32_e32 v164, v122, v122
	v_max_f32_e32 v163, v164, v163
	v_max3_f32 v163, v120, v121, v163
	v_max3_f32 v161, v161, v162, v163
	v_mov_b32_e32 v162, v161
	s_nop 1
	v_permlane16_swap_b32_e32 v161, v162
	v_max_f32_e32 v162, v162, v162
	v_max_f32_e32 v161, v161, v161
	v_max_f32_e32 v161, v161, v162
	v_mov_b32_e32 v162, v161
	s_nop 1
	v_permlane32_swap_b32_e32 v161, v162
	v_max_f32_e32 v162, v162, v162
	v_max_f32_e32 v161, v161, v161
	v_max_f32_e32 v161, v161, v162
	v_sub_f32_e32 v162, v161, v133
	v_cmp_lt_f32_e32 vcc, s4, v162
	s_cbranch_vccz .LBB0_182
	v_max_f32_e32 v161, v161, v161
	v_max_f32_e32 v162, v133, v133
	v_max_f32_e32 v161, v162, v161
	v_sub_f32_e32 v133, v133, v161
	v_exp_f32_e32 v162, v133
	v_mov_b32_e32 v133, v161
	v_mul_f32_e32 v141, v141, v162
	v_mul_f32_e64 v74, v74, v162
	v_mul_f32_e64 v75, v75, v162
	v_mul_f32_e64 v72, v72, v162
	v_mul_f32_e64 v73, v73, v162
	v_mul_f32_e64 v70, v70, v162
	v_mul_f32_e64 v71, v71, v162
	v_mul_f32_e64 v68, v68, v162
	v_mul_f32_e64 v69, v69, v162
	v_mul_f32_e64 v66, v66, v162
	v_mul_f32_e64 v67, v67, v162
	v_mul_f32_e64 v64, v64, v162
	v_mul_f32_e64 v65, v65, v162
	v_mul_f32_e64 v54, v54, v162
	v_mul_f32_e64 v55, v55, v162
	v_mul_f32_e64 v52, v52, v162
	v_mul_f32_e64 v53, v53, v162
.LBB0_182:
	v_mfma_f32_16x16x32_bf16 v[92:95], v[92:95], v[8:11], 0
	v_sub_f32_e32 v117, v117, v133
	v_exp_f32_e32 v161, v117
	v_sub_f32_e32 v117, v118, v133
	v_mfma_f32_16x16x32_bf16 v[92:95], v[96:99], v[4:7], v[92:95]
	v_sub_f32_e32 v118, v119, v133
	v_sub_f32_e32 v119, v120, v133
	v_exp_f32_e32 v120, v119
	v_mfma_f32_16x16x32_bf16 v[96:99], v[112:115], v[8:11], 0
	v_sub_f32_e32 v119, v121, v133
	v_exp_f32_e32 v162, v119
	v_sub_f32_e32 v119, v122, v133
	v_mfma_f32_16x16x32_bf16 v[96:99], v[104:107], v[4:7], v[96:99]
	v_sub_f32_e32 v116, v116, v133
	v_exp_f32_e32 v121, v119
	v_sub_f32_e32 v119, v123, v133
	v_mfma_f32_16x16x32_bf16 v[96:99], v[100:103], v[0:3], v[96:99]
	v_exp_f32_e32 v116, v116
	v_exp_f32_e32 v117, v117
	v_exp_f32_e32 v118, v118
	v_mfma_f32_16x16x32_bf16 v[92:95], v[108:111], v[0:3], v[92:95]
	v_exp_f32_e32 v122, v119
	s_nop 2
	v_max_f32_e32 v100, v99, v99
	v_max_f32_e32 v101, v98, v98
	v_max_f32_e32 v100, v101, v100
	v_max3_f32 v100, v96, v97, v100
	v_max_f32_e32 v108, v93, v93
	v_max_f32_e32 v109, v92, v92
	v_max_f32_e32 v104, v95, v95
	v_max_f32_e32 v105, v94, v94
	v_max_f32_e32 v108, v109, v108
	v_max_f32_e32 v104, v105, v104
	v_max3_f32 v100, v108, v104, v100
	v_mov_b32_e32 v101, v100
	s_nop 1
	v_permlane16_swap_b32_e32 v100, v101
	v_max_f32_e32 v101, v101, v101
	v_max_f32_e32 v100, v100, v100
	v_max_f32_e32 v100, v100, v101
	v_mov_b32_e32 v101, v100
	s_nop 1
	v_permlane32_swap_b32_e32 v100, v101
	v_cvt_pk_bf16_f32 v164, v116, v161
	v_cvt_pk_bf16_f32 v165, v117, v118
	v_cvt_pk_bf16_f32 v166, v120, v162
	v_cvt_pk_bf16_f32 v167, v121, v122
	v_max_f32_e32 v101, v101, v101
	s_waitcnt lgkmcnt(3)
	v_mfma_f32_16x16x32_bf16 v[72:75], v[80:83], v[164:167], v[72:75]
	v_max_f32_e32 v100, v100, v100
	v_max_f32_e32 v100, v100, v101
	v_sub_f32_e32 v101, v100, v131
	s_waitcnt lgkmcnt(2)
	v_mfma_f32_16x16x32_bf16 v[68:71], v[84:87], v[164:167], v[68:71]
	v_cmp_lt_f32_e32 vcc, s4, v101
	s_waitcnt lgkmcnt(1)
	v_mfma_f32_16x16x32_bf16 v[64:67], v[88:91], v[164:167], v[64:67]
	s_waitcnt lgkmcnt(0)
	v_mfma_f32_16x16x32_bf16 v[52:55], v[76:79], v[164:167], v[52:55]
	s_cbranch_vccz .LBB0_184
	v_max_f32_e32 v100, v100, v100
	v_max_f32_e32 v101, v131, v131
	v_max_f32_e32 v101, v101, v100
	v_sub_f32_e32 v100, v131, v101
	v_exp_f32_e32 v100, v100
	v_mov_b32_e32 v131, v101
	v_mul_f32_e32 v135, v135, v100
	v_mul_f32_e64 v30, v30, v100
	v_mul_f32_e64 v31, v31, v100
	v_mul_f32_e64 v28, v28, v100
	v_mul_f32_e64 v29, v29, v100
	v_mul_f32_e64 v34, v34, v100
	v_mul_f32_e64 v35, v35, v100
	v_mul_f32_e64 v32, v32, v100
	v_mul_f32_e64 v33, v33, v100
	v_mul_f32_e64 v38, v38, v100
	v_mul_f32_e64 v39, v39, v100
	v_mul_f32_e64 v36, v36, v100
	v_mul_f32_e64 v37, v37, v100
	v_mul_f32_e64 v26, v26, v100
	v_mul_f32_e64 v27, v27, v100
	v_mul_f32_e64 v24, v24, v100
	v_mul_f32_e64 v25, v25, v100
.LBB0_184:
	ds_read_b128 v[100:103], v159 offset:6656
	v_sub_f32_e32 v92, v92, v131
	v_exp_f32_e32 v163, v92
	v_sub_f32_e32 v92, v93, v131
	v_exp_f32_e32 v164, v92
	v_sub_f32_e32 v92, v94, v131
	v_exp_f32_e32 v165, v92
	v_sub_f32_e32 v92, v95, v131
	v_exp_f32_e32 v166, v92
	v_sub_f32_e32 v92, v96, v131
	v_exp_f32_e32 v167, v92
	v_sub_f32_e32 v92, v97, v131
	v_exp_f32_e32 v168, v92
	v_sub_f32_e32 v92, v98, v131
	v_exp_f32_e32 v169, v92
	v_sub_f32_e32 v92, v99, v131
	v_exp_f32_e32 v201, v92
	v_cvt_pk_bf16_f32 v92, v163, v164
	v_cvt_pk_bf16_f32 v93, v165, v166
	v_cvt_pk_bf16_f32 v94, v167, v168
	v_cvt_pk_bf16_f32 v95, v169, v201
	ds_read_b128 v[104:107], v159 offset:6720
	ds_read_b128 v[108:111], v159 offset:6784
	v_mfma_f32_16x16x32_bf16 v[24:27], v[76:79], v[92:95], v[24:27]
	ds_read_b128 v[112:115], v159 offset:9984
	ds_read_b128 v[96:99], v159 offset:10048
	s_waitcnt lgkmcnt(4)
	v_mfma_f32_16x16x32_bf16 v[76:79], v[100:103], v[20:23], 0
	v_mfma_f32_16x16x32_bf16 v[28:31], v[80:83], v[92:95], v[28:31]
	v_add_f32_e32 v80, 0, v116
	v_add_f32_e32 v80, v161, v80
	v_add_f32_e32 v80, v117, v80
	s_waitcnt lgkmcnt(3)
	v_mfma_f32_16x16x32_bf16 v[76:79], v[104:107], v[12:15], v[76:79]
	v_add_f32_e32 v80, v118, v80
	v_mfma_f32_16x16x32_bf16 v[32:35], v[84:87], v[92:95], v[32:35]
	v_mfma_f32_16x16x32_bf16 v[36:39], v[88:91], v[92:95], v[36:39]
	ds_read_b128 v[92:95], v159 offset:10112
	s_waitcnt lgkmcnt(3)
	v_mfma_f32_16x16x32_bf16 v[116:119], v[108:111], v[16:19], v[76:79]
	s_nop 2
	v_add_f32_e32 v76, v120, v80
	v_add_f32_e32 v80, v162, v76
	s_waitcnt lgkmcnt(2)
	v_mfma_f32_16x16x32_bf16 v[76:79], v[112:115], v[20:23], 0
	v_add_f32_e32 v80, v121, v80
	v_add_f32_e32 v80, v122, v80
	v_add_f32_e32 v141, v141, v80
	s_waitcnt lgkmcnt(1)
	v_mfma_f32_16x16x32_bf16 v[120:123], v[96:99], v[12:15], v[76:79]
	ds_read_b128 v[88:91], v160 offset:13376
	ds_read_b128 v[84:87], v160 offset:15680
	ds_read_b128 v[80:83], v160 offset:17984
	ds_read_b128 v[76:79], v160 offset:20288
	v_max_f32_e32 v159, v117, v117
	v_max_f32_e32 v160, v116, v116
	s_waitcnt lgkmcnt(4)
	v_mfma_f32_16x16x32_bf16 v[120:123], v[92:95], v[16:19], v[120:123]
	v_max_f32_e32 v159, v160, v159
	v_max_f32_e32 v160, v119, v119
	v_max_f32_e32 v161, v118, v118
	v_max_f32_e32 v160, v161, v160
	s_nop 3
	v_max_f32_e32 v161, v123, v123
	v_max_f32_e32 v162, v122, v122
	v_max_f32_e32 v161, v162, v161
	v_max3_f32 v161, v120, v121, v161
	v_max3_f32 v159, v159, v160, v161
	v_mov_b32_e32 v160, v159
	s_nop 1
	v_permlane16_swap_b32_e32 v159, v160
	v_max_f32_e32 v160, v160, v160
	v_max_f32_e32 v159, v159, v159
	v_max_f32_e32 v159, v159, v160
	v_mov_b32_e32 v160, v159
	s_nop 1
	v_permlane32_swap_b32_e32 v159, v160
	v_max_f32_e32 v160, v160, v160
	v_max_f32_e32 v159, v159, v159
	v_max_f32_e32 v159, v159, v160
	v_sub_f32_e32 v160, v159, v133
	v_cmp_lt_f32_e32 vcc, s4, v160
	s_cbranch_vccz .LBB0_186
	v_max_f32_e32 v159, v159, v159
	v_max_f32_e32 v160, v133, v133
	v_max_f32_e32 v159, v160, v159
	v_sub_f32_e32 v133, v133, v159
	v_exp_f32_e32 v160, v133
	v_mov_b32_e32 v133, v159
	v_mul_f32_e32 v141, v141, v160
	v_mul_f32_e64 v74, v74, v160
	v_mul_f32_e64 v75, v75, v160
	v_mul_f32_e64 v72, v72, v160
	v_mul_f32_e64 v73, v73, v160
	v_mul_f32_e64 v70, v70, v160
	v_mul_f32_e64 v71, v71, v160
	v_mul_f32_e64 v68, v68, v160
	v_mul_f32_e64 v69, v69, v160
	v_mul_f32_e64 v66, v66, v160
	v_mul_f32_e64 v67, v67, v160
	v_mul_f32_e64 v64, v64, v160
	v_mul_f32_e64 v65, v65, v160
	v_mul_f32_e64 v54, v54, v160
	v_mul_f32_e64 v55, v55, v160
	v_mul_f32_e64 v52, v52, v160
	v_mul_f32_e64 v53, v53, v160
.LBB0_186:
	v_mfma_f32_16x16x32_bf16 v[100:103], v[100:103], v[8:11], 0
	v_add_f32_e32 v159, 0, v163
	v_add_f32_e32 v159, v164, v159
	v_add_f32_e32 v159, v165, v159
	v_mfma_f32_16x16x32_bf16 v[100:103], v[104:107], v[4:7], v[100:103]
	v_add_f32_e32 v159, v166, v159
	v_add_f32_e32 v159, v167, v159
	v_sub_f32_e32 v116, v116, v133
	v_mfma_f32_16x16x32_bf16 v[104:107], v[112:115], v[8:11], 0
	v_sub_f32_e32 v117, v117, v133
	v_sub_f32_e32 v118, v118, v133
	v_sub_f32_e32 v119, v119, v133
	v_mfma_f32_16x16x32_bf16 v[96:99], v[96:99], v[4:7], v[104:107]
	v_sub_f32_e32 v120, v120, v133
	v_sub_f32_e32 v121, v121, v133
	v_sub_f32_e32 v122, v122, v133
	v_mfma_f32_16x16x32_bf16 v[100:103], v[108:111], v[0:3], v[100:103]
	v_sub_f32_e32 v123, v123, v133
	v_add_f32_e32 v159, v168, v159
	v_exp_f32_e32 v116, v116
	v_mfma_f32_16x16x32_bf16 v[92:95], v[92:95], v[0:3], v[96:99]
	v_exp_f32_e32 v117, v117
	v_exp_f32_e32 v118, v118
	v_exp_f32_e32 v119, v119
	s_nop 0
	v_max_f32_e32 v96, v101, v101
	v_max_f32_e32 v97, v100, v100
	v_max_f32_e32 v96, v97, v96
	v_max_f32_e32 v97, v103, v103
	v_max_f32_e32 v98, v102, v102
	v_max_f32_e32 v97, v98, v97
	v_max_f32_e32 v98, v95, v95
	v_max_f32_e32 v99, v94, v94
	v_max_f32_e32 v98, v99, v98
	v_max3_f32 v98, v92, v93, v98
	v_max3_f32 v96, v96, v97, v98
	v_mov_b32_e32 v97, v96
	s_nop 1
	v_permlane16_swap_b32_e32 v96, v97
	v_max_f32_e32 v97, v97, v97
	v_max_f32_e32 v96, v96, v96
	v_max_f32_e32 v96, v96, v97
	v_mov_b32_e32 v97, v96
	s_nop 1
	v_permlane32_swap_b32_e32 v96, v97
	v_exp_f32_e32 v120, v120
	v_exp_f32_e32 v121, v121
	v_exp_f32_e32 v122, v122
	v_exp_f32_e32 v123, v123
	v_cvt_pk_bf16_f32 v160, v116, v117
	v_cvt_pk_bf16_f32 v161, v118, v119
	v_cvt_pk_bf16_f32 v162, v120, v121
	v_cvt_pk_bf16_f32 v163, v122, v123
	v_max_f32_e32 v97, v97, v97
	s_waitcnt lgkmcnt(3)
	v_mfma_f32_16x16x32_bf16 v[72:75], v[88:91], v[160:163], v[72:75]
	v_max_f32_e32 v96, v96, v96
	v_add_f32_e32 v159, v169, v159
	v_max_f32_e32 v96, v96, v97
	s_waitcnt lgkmcnt(2)
	v_mfma_f32_16x16x32_bf16 v[68:71], v[84:87], v[160:163], v[68:71]
	v_add_f32_e32 v159, v201, v159
	v_sub_f32_e32 v97, v96, v131
	v_add_f32_e32 v135, v135, v159
	s_waitcnt lgkmcnt(1)
	v_mfma_f32_16x16x32_bf16 v[64:67], v[80:83], v[160:163], v[64:67]
	v_cmp_lt_f32_e32 vcc, s4, v97
	s_waitcnt lgkmcnt(0)
	v_mfma_f32_16x16x32_bf16 v[52:55], v[76:79], v[160:163], v[52:55]
	s_cbranch_vccz .LBB0_179
	v_max_f32_e32 v96, v96, v96
	v_max_f32_e32 v97, v131, v131
	v_max_f32_e32 v97, v97, v96
	v_sub_f32_e32 v96, v131, v97
	v_exp_f32_e32 v96, v96
	v_mov_b32_e32 v131, v97
	v_mul_f32_e32 v135, v135, v96
	v_mul_f32_e64 v30, v30, v96
	v_mul_f32_e64 v31, v31, v96
	v_mul_f32_e64 v28, v28, v96
	v_mul_f32_e64 v29, v29, v96
	v_mul_f32_e64 v34, v34, v96
	v_mul_f32_e64 v35, v35, v96
	v_mul_f32_e64 v32, v32, v96
	v_mul_f32_e64 v33, v33, v96
	v_mul_f32_e64 v38, v38, v96
	v_mul_f32_e64 v39, v39, v96
	v_mul_f32_e64 v36, v36, v96
	v_mul_f32_e64 v37, v37, v96
	v_mul_f32_e64 v26, v26, v96
	v_mul_f32_e64 v27, v27, v96
	v_mul_f32_e64 v24, v24, v96
	v_mul_f32_e64 v25, v25, v96
	s_branch .LBB0_179
.LBB0_188:
	v_add_u32_e32 v105, v128, v158
	ds_read_b128 v[84:87], v105 offset:22528
	ds_read_b128 v[88:91], v105 offset:22592
	ds_read_b128 v[92:95], v105 offset:22656
	ds_read_b128 v[96:99], v105 offset:25856
	ds_read_b128 v[80:83], v105 offset:25920
	ds_read_b128 v[76:79], v105 offset:25984
	s_waitcnt lgkmcnt(5)
	v_mfma_f32_16x16x32_bf16 v[60:63], v[84:87], v[20:23], 0
	v_add_u32_e32 v104, v128, v157
	ds_read_b128 v[44:47], v104 offset:35840
	ds_read_b128 v[48:51], v104 offset:38144
	ds_read_b128 v[56:59], v104 offset:40448
	ds_read_b128 v[40:43], v104 offset:42752
	s_waitcnt lgkmcnt(6)
	v_mfma_f32_16x16x32_bf16 v[100:103], v[96:99], v[20:23], 0
	v_mfma_f32_16x16x32_bf16 v[60:63], v[88:91], v[12:15], v[60:63]
	s_waitcnt lgkmcnt(5)
	v_mfma_f32_16x16x32_bf16 v[100:103], v[80:83], v[12:15], v[100:103]
	v_mfma_f32_16x16x32_bf16 v[60:63], v[92:95], v[16:19], v[60:63]
	s_waitcnt lgkmcnt(4)
	v_mfma_f32_16x16x32_bf16 v[100:103], v[76:79], v[16:19], v[100:103]
	s_nop 5
	v_max_f32_e32 v106, v61, v61
	v_max_f32_e32 v107, v60, v60
	v_max_f32_e32 v106, v107, v106
	v_max_f32_e32 v107, v63, v63
	v_max_f32_e32 v108, v62, v62
	v_max_f32_e32 v107, v108, v107
	v_max_f32_e32 v108, v103, v103
	v_max_f32_e32 v109, v102, v102
	v_max_f32_e32 v108, v109, v108
	v_max3_f32 v108, v100, v101, v108
	v_max3_f32 v106, v106, v107, v108
	v_mov_b32_e32 v107, v106
	s_nop 1
	v_permlane16_swap_b32_e32 v106, v107
	v_max_f32_e32 v107, v107, v107
	v_max_f32_e32 v106, v106, v106
	v_max_f32_e32 v106, v106, v107
	v_mov_b32_e32 v107, v106
	s_nop 1
	v_permlane32_swap_b32_e32 v106, v107
	v_max_f32_e32 v107, v107, v107
	v_max_f32_e32 v106, v106, v106
	v_max_f32_e32 v106, v106, v107
	v_sub_f32_e32 v107, v106, v133
	v_cmp_lt_f32_e32 vcc, s4, v107
	s_cbranch_vccz .LBB0_190
	v_max_f32_e32 v106, v106, v106
	v_max_f32_e32 v107, v133, v133
	v_max_f32_e32 v107, v107, v106
	v_sub_f32_e32 v106, v133, v107
	v_exp_f32_e32 v106, v106
	v_mov_b32_e32 v133, v107
	v_mul_f32_e32 v141, v141, v106
	v_mul_f32_e64 v74, v74, v106
	v_mul_f32_e64 v75, v75, v106
	v_mul_f32_e64 v72, v72, v106
	v_mul_f32_e64 v73, v73, v106
	v_mul_f32_e64 v70, v70, v106
	v_mul_f32_e64 v71, v71, v106
	v_mul_f32_e64 v68, v68, v106
	v_mul_f32_e64 v69, v69, v106
	v_mul_f32_e64 v66, v66, v106
	v_mul_f32_e64 v67, v67, v106
	v_mul_f32_e64 v64, v64, v106
	v_mul_f32_e64 v65, v65, v106
	v_mul_f32_e64 v54, v54, v106
	v_mul_f32_e64 v55, v55, v106
	v_mul_f32_e64 v52, v52, v106
	v_mul_f32_e64 v53, v53, v106
.LBB0_190:
	v_sub_f32_e32 v60, v60, v133
	v_exp_f32_e32 v106, v60
	v_sub_f32_e32 v60, v61, v133
	v_exp_f32_e32 v108, v60
	v_sub_f32_e32 v60, v62, v133
	v_exp_f32_e32 v107, v60
	v_sub_f32_e32 v60, v63, v133
	v_exp_f32_e32 v109, v60
	v_sub_f32_e32 v60, v100, v133
	v_exp_f32_e32 v100, v60
	v_sub_f32_e32 v60, v101, v133
	v_exp_f32_e32 v110, v60
	v_sub_f32_e32 v60, v102, v133
	v_exp_f32_e32 v101, v60
	v_sub_f32_e32 v60, v103, v133
	v_exp_f32_e32 v102, v60
	v_cvt_pk_bf16_f32 v112, v106, v108
	v_cvt_pk_bf16_f32 v113, v107, v109
	v_cvt_pk_bf16_f32 v114, v100, v110
	v_cvt_pk_bf16_f32 v115, v101, v102
	s_waitcnt lgkmcnt(1)
	v_mfma_f32_16x16x32_bf16 v[60:63], v[56:59], v[112:115], v[64:67]
	v_mfma_f32_16x16x32_bf16 v[64:67], v[84:87], v[8:11], 0
	v_mfma_f32_16x16x32_bf16 v[84:87], v[96:99], v[8:11], 0
	v_mfma_f32_16x16x32_bf16 v[80:83], v[80:83], v[4:7], v[84:87]
	v_mfma_f32_16x16x32_bf16 v[64:67], v[88:91], v[4:7], v[64:67]
	v_mfma_f32_16x16x32_bf16 v[76:79], v[76:79], v[0:3], v[80:83]
	v_mfma_f32_16x16x32_bf16 v[64:67], v[92:95], v[0:3], v[64:67]
	v_mfma_f32_16x16x32_bf16 v[72:75], v[44:47], v[112:115], v[72:75]
	s_nop 5
	v_max_f32_e32 v80, v79, v79
	v_max_f32_e32 v81, v78, v78
	v_max_f32_e32 v88, v65, v65
	v_max_f32_e32 v89, v64, v64
	v_max_f32_e32 v84, v67, v67
	v_max_f32_e32 v85, v66, v66
	v_max_f32_e32 v80, v81, v80
	v_max_f32_e32 v88, v89, v88
	v_max_f32_e32 v84, v85, v84
	v_max3_f32 v80, v76, v77, v80
	v_max3_f32 v80, v88, v84, v80
	v_mov_b32_e32 v81, v80
	s_nop 1
	v_permlane16_swap_b32_e32 v80, v81
	v_max_f32_e32 v81, v81, v81
	v_max_f32_e32 v80, v80, v80
	v_max_f32_e32 v80, v80, v81
	v_mov_b32_e32 v81, v80
	s_nop 1
	v_permlane32_swap_b32_e32 v80, v81
	v_mfma_f32_16x16x32_bf16 v[68:71], v[48:51], v[112:115], v[68:71]
	v_max_f32_e32 v81, v81, v81
	v_max_f32_e32 v80, v80, v80
	v_max_f32_e32 v80, v80, v81
	s_waitcnt lgkmcnt(0)
	v_mfma_f32_16x16x32_bf16 v[52:55], v[40:43], v[112:115], v[52:55]
	v_sub_f32_e32 v81, v80, v131
	v_cmp_lt_f32_e32 vcc, s4, v81
	s_cbranch_vccz .LBB0_192
	v_max_f32_e32 v80, v80, v80
	v_max_f32_e32 v81, v131, v131
	v_max_f32_e32 v81, v81, v80
	v_sub_f32_e32 v80, v131, v81
	v_exp_f32_e32 v80, v80
	v_mov_b32_e32 v131, v81
	v_mul_f32_e32 v135, v135, v80
	v_mul_f32_e64 v30, v30, v80
	v_mul_f32_e64 v31, v31, v80
	v_mul_f32_e64 v28, v28, v80
	v_mul_f32_e64 v29, v29, v80
	v_mul_f32_e64 v34, v34, v80
	v_mul_f32_e64 v35, v35, v80
	v_mul_f32_e64 v32, v32, v80
	v_mul_f32_e64 v33, v33, v80
	v_mul_f32_e64 v38, v38, v80
	v_mul_f32_e64 v39, v39, v80
	v_mul_f32_e64 v36, v36, v80
	v_mul_f32_e64 v37, v37, v80
	v_mul_f32_e64 v26, v26, v80
	v_mul_f32_e64 v27, v27, v80
	v_mul_f32_e64 v24, v24, v80
	v_mul_f32_e64 v25, v25, v80
.LBB0_192:
	ds_read_b128 v[84:87], v105 offset:29184
	ds_read_b128 v[88:91], v105 offset:29248
	ds_read_b128 v[92:95], v105 offset:29312
	ds_read_b128 v[96:99], v105 offset:32512
	ds_read_b128 v[80:83], v105 offset:32576
	v_sub_f32_e32 v76, v76, v131
	v_exp_f32_e32 v103, v76
	v_sub_f32_e32 v76, v77, v131
	v_exp_f32_e32 v111, v76
	v_sub_f32_e32 v76, v78, v131
	v_sub_f32_e32 v64, v64, v131
	v_sub_f32_e32 v65, v65, v131
	v_sub_f32_e32 v66, v66, v131
	v_sub_f32_e32 v67, v67, v131
	v_exp_f32_e32 v112, v76
	v_sub_f32_e32 v76, v79, v131
	v_exp_f32_e32 v64, v64
	v_exp_f32_e32 v65, v65
	v_exp_f32_e32 v66, v66
	v_exp_f32_e32 v67, v67
	v_exp_f32_e32 v113, v76
	v_cvt_pk_bf16_f32 v76, v64, v65
	v_cvt_pk_bf16_f32 v77, v66, v67
	v_cvt_pk_bf16_f32 v78, v103, v111
	v_cvt_pk_bf16_f32 v79, v112, v113
	s_nop 0
	v_mfma_f32_16x16x32_bf16 v[44:47], v[44:47], v[76:79], v[28:31]
	v_mfma_f32_16x16x32_bf16 v[28:31], v[56:59], v[76:79], v[36:39]
	s_waitcnt lgkmcnt(4)
	v_mfma_f32_16x16x32_bf16 v[36:39], v[84:87], v[20:23], 0
	v_mfma_f32_16x16x32_bf16 v[32:35], v[48:51], v[76:79], v[32:35]
	v_mfma_f32_16x16x32_bf16 v[24:27], v[40:43], v[76:79], v[24:27]
	ds_read_b128 v[76:79], v105 offset:32640
	v_add_f32_e32 v40, 0, v106
	v_add_f32_e32 v40, v108, v40
	s_waitcnt lgkmcnt(2)
	v_mfma_f32_16x16x32_bf16 v[20:23], v[96:99], v[20:23], 0
	v_add_f32_e32 v40, v107, v40
	v_add_f32_e32 v40, v109, v40
	v_mfma_f32_16x16x32_bf16 v[36:39], v[88:91], v[12:15], v[36:39]
	s_waitcnt lgkmcnt(1)
	v_mfma_f32_16x16x32_bf16 v[56:59], v[80:83], v[12:15], v[20:23]
	v_mfma_f32_16x16x32_bf16 v[48:51], v[92:95], v[16:19], v[36:39]
	s_waitcnt lgkmcnt(0)
	v_mfma_f32_16x16x32_bf16 v[16:19], v[76:79], v[16:19], v[56:59]
	s_nop 2
	v_add_f32_e32 v36, v100, v40
	v_add_f32_e32 v36, v110, v36
	v_add_f32_e32 v36, v101, v36
	v_max_f32_e32 v56, v49, v49
	v_max_f32_e32 v57, v48, v48
	v_max_f32_e32 v56, v57, v56
	v_max_f32_e32 v57, v51, v51
	v_max_f32_e32 v58, v50, v50
	v_max_f32_e32 v57, v58, v57
	v_max_f32_e32 v58, v19, v19
	v_max_f32_e32 v59, v18, v18
	v_max_f32_e32 v58, v59, v58
	v_max3_f32 v58, v16, v17, v58
	v_max3_f32 v56, v56, v57, v58
	v_mov_b32_e32 v57, v56
	s_nop 1
	v_permlane16_swap_b32_e32 v56, v57
	v_add_f32_e32 v36, v102, v36
	v_max_f32_e32 v57, v57, v57
	v_max_f32_e32 v56, v56, v56
	v_add_f32_e32 v100, v141, v36
	ds_read_b128 v[12:15], v104 offset:35904
	ds_read_b128 v[20:23], v104 offset:38208
	ds_read_b128 v[36:39], v104 offset:40512
	ds_read_b128 v[40:43], v104 offset:42816
	v_max_f32_e32 v56, v56, v57
	v_mov_b32_e32 v57, v56
	s_nop 1
	v_permlane32_swap_b32_e32 v56, v57
	v_max_f32_e32 v57, v57, v57
	v_max_f32_e32 v56, v56, v56
	v_max_f32_e32 v56, v56, v57
	v_sub_f32_e32 v57, v56, v133
	v_cmp_lt_f32_e32 vcc, s4, v57
	s_cbranch_vccz .LBB0_194
	v_max_f32_e32 v56, v56, v56
	v_max_f32_e32 v57, v133, v133
	v_max_f32_e32 v57, v57, v56
	v_sub_f32_e32 v56, v133, v57
	v_exp_f32_e32 v56, v56
	v_mov_b32_e32 v133, v57
	v_mul_f32_e32 v100, v100, v56
	v_mul_f32_e64 v74, v74, v56
	v_mul_f32_e64 v75, v75, v56
	v_mul_f32_e64 v72, v72, v56
	v_mul_f32_e64 v73, v73, v56
	v_mul_f32_e64 v70, v70, v56
	v_mul_f32_e64 v71, v71, v56
	v_mul_f32_e64 v68, v68, v56
	v_mul_f32_e64 v69, v69, v56
	v_mul_f32_e64 v62, v62, v56
	v_mul_f32_e64 v63, v63, v56
	v_mul_f32_e64 v60, v60, v56
	v_mul_f32_e64 v61, v61, v56
	v_mul_f32_e64 v54, v54, v56
	v_mul_f32_e64 v55, v55, v56
	v_mul_f32_e64 v52, v52, v56
	v_mul_f32_e64 v53, v53, v56
.LBB0_194:
	v_add_f32_e32 v56, 0, v64
	v_add_f32_e32 v56, v65, v56
	v_add_f32_e32 v56, v66, v56
	v_add_f32_e32 v56, v67, v56
	v_sub_f32_e32 v48, v48, v133
	v_sub_f32_e32 v16, v16, v133
	v_add_f32_e32 v56, v103, v56
	v_exp_f32_e32 v102, v48
	v_sub_f32_e32 v48, v49, v133
	v_exp_f32_e32 v106, v16
	v_sub_f32_e32 v16, v17, v133
	v_add_f32_e32 v56, v111, v56
	v_exp_f32_e32 v103, v48
	v_sub_f32_e32 v48, v50, v133
	v_exp_f32_e32 v107, v16
	v_sub_f32_e32 v16, v18, v133
	v_add_f32_e32 v56, v112, v56
	v_exp_f32_e32 v104, v48
	v_sub_f32_e32 v48, v51, v133
	v_exp_f32_e32 v108, v16
	v_sub_f32_e32 v16, v19, v133
	v_add_f32_e32 v56, v113, v56
	v_exp_f32_e32 v105, v48
	v_exp_f32_e32 v109, v16
	v_cvt_pk_bf16_f32 v16, v102, v103
	v_cvt_pk_bf16_f32 v17, v104, v105
	v_cvt_pk_bf16_f32 v18, v106, v107
	v_cvt_pk_bf16_f32 v19, v108, v109
	v_add_f32_e32 v101, v135, v56
	s_waitcnt lgkmcnt(3)
	v_mfma_f32_16x16x32_bf16 v[64:67], v[12:15], v[16:19], v[72:75]
	s_waitcnt lgkmcnt(2)
	v_mfma_f32_16x16x32_bf16 v[56:59], v[20:23], v[16:19], v[68:71]
	s_waitcnt lgkmcnt(1)
	v_mfma_f32_16x16x32_bf16 v[48:51], v[36:39], v[16:19], v[60:63]
	s_waitcnt lgkmcnt(0)
	v_mfma_f32_16x16x32_bf16 v[16:19], v[40:43], v[16:19], v[52:55]
	v_mfma_f32_16x16x32_bf16 v[52:55], v[84:87], v[8:11], 0
	v_mfma_f32_16x16x32_bf16 v[8:11], v[96:99], v[8:11], 0
	v_mfma_f32_16x16x32_bf16 v[52:55], v[88:91], v[4:7], v[52:55]
	v_mfma_f32_16x16x32_bf16 v[4:7], v[80:83], v[4:7], v[8:11]
	v_mfma_f32_16x16x32_bf16 v[52:55], v[92:95], v[0:3], v[52:55]
	v_mfma_f32_16x16x32_bf16 v[0:3], v[76:79], v[0:3], v[4:7]
	s_nop 6
	v_max_f32_e32 v4, v53, v53
	v_max_f32_e32 v5, v52, v52
	v_max_f32_e32 v4, v5, v4
	v_max_f32_e32 v5, v55, v55
	v_max_f32_e32 v6, v54, v54
	v_max_f32_e32 v5, v6, v5
	v_max_f32_e32 v6, v3, v3
	v_max_f32_e32 v7, v2, v2
	v_max_f32_e32 v6, v7, v6
	v_max3_f32 v6, v0, v1, v6
	v_max3_f32 v4, v4, v5, v6
	v_mov_b32_e32 v5, v4
	s_nop 1
	v_permlane16_swap_b32_e32 v4, v5
	v_max_f32_e32 v5, v5, v5
	v_max_f32_e32 v4, v4, v4
	v_max_f32_e32 v4, v4, v5
	v_mov_b32_e32 v5, v4
	s_nop 1
	v_permlane32_swap_b32_e32 v4, v5
	v_max_f32_e32 v5, v5, v5
	v_max_f32_e32 v4, v4, v4
	v_max_f32_e32 v4, v4, v5
	v_sub_f32_e32 v5, v4, v131
	v_cmp_lt_f32_e32 vcc, s4, v5
	s_cbranch_vccz .LBB0_196
	v_max_f32_e32 v4, v4, v4
	v_max_f32_e32 v5, v131, v131
	v_max_f32_e32 v5, v5, v4
	v_sub_f32_e32 v4, v131, v5
	v_exp_f32_e32 v4, v4
	v_mov_b32_e32 v131, v5
	v_mul_f32_e32 v101, v101, v4
	v_mul_f32_e64 v46, v46, v4
	v_mul_f32_e64 v47, v47, v4
	v_mul_f32_e64 v44, v44, v4
	v_mul_f32_e64 v45, v45, v4
	v_mul_f32_e64 v34, v34, v4
	v_mul_f32_e64 v35, v35, v4
	v_mul_f32_e64 v32, v32, v4
	v_mul_f32_e64 v33, v33, v4
	v_mul_f32_e64 v30, v30, v4
	v_mul_f32_e64 v31, v31, v4
	v_mul_f32_e64 v28, v28, v4
	v_mul_f32_e64 v29, v29, v4
	v_mul_f32_e64 v26, v26, v4
	v_mul_f32_e64 v27, v27, v4
	v_mul_f32_e64 v24, v24, v4
	v_mul_f32_e64 v25, v25, v4

.LBB0_415:
	s_and_b32 s37, s36, 1
	s_cmp_lt_u32 s36, 63
	s_cselect_b64 vcc, -1, 0
	v_cndmask_b32_e32 v56, v141, v164, vcc
	v_add_u32_e32 v48, v56, v154
	v_ashrrev_i32_e32 v49, 31, v48
	v_lshlrev_b64 v[48:49], 2, v[48:49]
	s_movk_i32 s4, 0xc0
	v_or_b32_e32 v48, v48, v136
	v_add_u32_e32 v44, v56, v137
	v_mad_u64_u32 v[50:51], s[52:53], v48, s4, v[146:147]
	v_add_u32_e32 v48, v56, v155
	v_ashrrev_i32_e32 v45, 31, v44
	v_mad_i32_i24 v51, v49, s4, v51
	v_ashrrev_i32_e32 v49, 31, v48
	v_lshlrev_b64 v[44:45], 2, v[44:45]
	v_lshlrev_b64 v[48:49], 2, v[48:49]
	v_or_b32_e32 v44, v44, v136
	v_or_b32_e32 v48, v48, v136
	v_mad_u64_u32 v[46:47], s[52:53], v44, s4, v[144:145]
	v_mad_u64_u32 v[58:59], s[52:53], v48, s4, v[148:149]
	v_ashrrev_i32_e32 v57, 31, v56
	v_mad_i32_i24 v47, v45, s4, v47
	v_mad_i32_i24 v59, v49, s4, v59
	v_lshlrev_b64 v[56:57], 1, v[56:57]
	global_load_dwordx4 v[44:47], v[46:47], off
	s_nop 0
	global_load_dwordx4 v[52:55], v[50:51], off
	s_nop 0
	global_load_dwordx4 v[48:51], v[58:59], off
	v_lshl_add_u64 v[58:59], v[150:151], 0, v[56:57]
	v_lshl_add_u64 v[56:57], v[152:153], 0, v[56:57]
	global_load_dwordx4 v[60:63], v[58:59], off
	s_nop 0
	global_load_dwordx4 v[56:59], v[56:57], off
	s_mul_i32 s40, s37, 0x5800
	v_or_b32_e32 v80, s40, v128
	v_add_u32_e32 v165, v80, v163
	ds_read_b128 v[92:95], v165
	ds_read_b128 v[96:99], v165 offset:64
	ds_read_b128 v[108:111], v165 offset:128
	ds_read_b128 v[112:115], v165 offset:3328
	s_waitcnt lgkmcnt(3)
	v_mfma_f32_16x16x32_bf16 v[76:79], v[92:95], v[20:23], 0
	ds_read_b128 v[104:107], v165 offset:3392
	ds_read_b128 v[100:103], v165 offset:3456
	v_add_u32_e32 v166, v80, v162
	s_waitcnt lgkmcnt(4)
	v_mfma_f32_16x16x32_bf16 v[76:79], v[96:99], v[12:15], v[76:79]
	s_mov_b32 s4, 0x41000000
	s_waitcnt lgkmcnt(3)
	v_mfma_f32_16x16x32_bf16 v[116:119], v[108:111], v[16:19], v[76:79]
	s_waitcnt lgkmcnt(2)
	v_mfma_f32_16x16x32_bf16 v[76:79], v[112:115], v[20:23], 0
	s_waitcnt lgkmcnt(1)
	v_mfma_f32_16x16x32_bf16 v[120:123], v[104:107], v[12:15], v[76:79]
	s_nop 3
	v_max_f32_e32 v167, v117, v117
	v_max_f32_e32 v168, v116, v116
	v_max_f32_e32 v167, v168, v167
	s_waitcnt lgkmcnt(0)
	v_mfma_f32_16x16x32_bf16 v[120:123], v[100:103], v[16:19], v[120:123]
	v_max_f32_e32 v168, v119, v119
	v_max_f32_e32 v169, v118, v118
	v_max_f32_e32 v168, v169, v168
	ds_read_b128 v[80:83], v166 offset:13312
	ds_read_b128 v[84:87], v166 offset:15616
	ds_read_b128 v[88:91], v166 offset:17920
	ds_read_b128 v[76:79], v166 offset:20224
	s_nop 0
	v_max_f32_e32 v169, v123, v123
	v_max_f32_e32 v201, v122, v122
	v_max_f32_e32 v169, v201, v169
	v_max3_f32 v169, v120, v121, v169
	v_max3_f32 v167, v167, v168, v169
	v_mov_b32_e32 v168, v167
	s_nop 1
	v_permlane16_swap_b32_e32 v167, v168
	v_max_f32_e32 v168, v168, v168
	v_max_f32_e32 v167, v167, v167
	v_max_f32_e32 v167, v167, v168
	v_mov_b32_e32 v168, v167
	s_nop 1
	v_permlane32_swap_b32_e32 v167, v168
	v_max_f32_e32 v168, v168, v168
	v_max_f32_e32 v167, v167, v167
	v_max_f32_e32 v167, v167, v168
	v_sub_f32_e32 v168, v167, v133
	v_cmp_lt_f32_e32 vcc, s4, v168
	s_cbranch_vccz .LBB0_417
	v_max_f32_e32 v167, v167, v167
	v_max_f32_e32 v168, v133, v133
	v_max_f32_e32 v167, v168, v167
	v_sub_f32_e32 v133, v133, v167
	v_exp_f32_e32 v168, v133
	v_mov_b32_e32 v133, v167
	v_mul_f32_e32 v139, v139, v168
	v_mul_f32_e64 v74, v74, v168
	v_mul_f32_e64 v75, v75, v168
	v_mul_f32_e64 v72, v72, v168
	v_mul_f32_e64 v73, v73, v168
	v_mul_f32_e64 v70, v70, v168
	v_mul_f32_e64 v71, v71, v168
	v_mul_f32_e64 v68, v68, v168
	v_mul_f32_e64 v69, v69, v168
	v_mul_f32_e64 v66, v66, v168
	v_mul_f32_e64 v67, v67, v168
	v_mul_f32_e64 v64, v64, v168
	v_mul_f32_e64 v65, v65, v168
	v_mul_f32_e64 v42, v42, v168
	v_mul_f32_e64 v43, v43, v168
	v_mul_f32_e64 v40, v40, v168
	v_mul_f32_e64 v41, v41, v168
.LBB0_417:
	v_mfma_f32_16x16x32_bf16 v[92:95], v[92:95], v[8:11], 0
	v_sub_f32_e32 v117, v117, v133
	v_exp_f32_e32 v167, v117
	v_sub_f32_e32 v117, v118, v133
	v_mfma_f32_16x16x32_bf16 v[92:95], v[96:99], v[4:7], v[92:95]
	v_sub_f32_e32 v118, v119, v133
	v_sub_f32_e32 v119, v120, v133
	v_exp_f32_e32 v120, v119
	v_mfma_f32_16x16x32_bf16 v[96:99], v[112:115], v[8:11], 0
	v_sub_f32_e32 v119, v121, v133
	v_exp_f32_e32 v168, v119
	v_sub_f32_e32 v119, v122, v133
	v_mfma_f32_16x16x32_bf16 v[96:99], v[104:107], v[4:7], v[96:99]
	v_sub_f32_e32 v116, v116, v133
	v_exp_f32_e32 v121, v119
	v_sub_f32_e32 v119, v123, v133
	v_mfma_f32_16x16x32_bf16 v[96:99], v[100:103], v[0:3], v[96:99]
	v_exp_f32_e32 v116, v116
	v_exp_f32_e32 v117, v117
	v_exp_f32_e32 v118, v118
	v_mfma_f32_16x16x32_bf16 v[92:95], v[108:111], v[0:3], v[92:95]
	v_exp_f32_e32 v122, v119
	s_nop 2
	v_max_f32_e32 v100, v99, v99
	v_max_f32_e32 v101, v98, v98
	v_max_f32_e32 v100, v101, v100
	v_max3_f32 v100, v96, v97, v100
	v_max_f32_e32 v108, v93, v93
	v_max_f32_e32 v109, v92, v92
	v_max_f32_e32 v104, v95, v95
	v_max_f32_e32 v105, v94, v94
	v_max_f32_e32 v108, v109, v108
	v_max_f32_e32 v104, v105, v104
	v_max3_f32 v100, v108, v104, v100
	v_mov_b32_e32 v101, v100
	s_nop 1
	v_permlane16_swap_b32_e32 v100, v101
	v_max_f32_e32 v101, v101, v101
	v_max_f32_e32 v100, v100, v100
	v_max_f32_e32 v100, v100, v101
	v_mov_b32_e32 v101, v100
	s_nop 1
	v_permlane32_swap_b32_e32 v100, v101
	v_cvt_pk_bf16_f32 v202, v116, v167
	v_cvt_pk_bf16_f32 v203, v117, v118
	v_cvt_pk_bf16_f32 v204, v120, v168
	v_cvt_pk_bf16_f32 v205, v121, v122
	v_max_f32_e32 v101, v101, v101
	s_waitcnt lgkmcnt(3)
	v_mfma_f32_16x16x32_bf16 v[72:75], v[80:83], v[202:205], v[72:75]
	v_max_f32_e32 v100, v100, v100
	v_max_f32_e32 v100, v100, v101
	v_sub_f32_e32 v101, v100, v131
	s_waitcnt lgkmcnt(2)
	v_mfma_f32_16x16x32_bf16 v[68:71], v[84:87], v[202:205], v[68:71]
	v_cmp_lt_f32_e32 vcc, s4, v101
	s_waitcnt lgkmcnt(1)
	v_mfma_f32_16x16x32_bf16 v[64:67], v[88:91], v[202:205], v[64:67]
	s_waitcnt lgkmcnt(0)
	v_mfma_f32_16x16x32_bf16 v[40:43], v[76:79], v[202:205], v[40:43]
	s_cbranch_vccz .LBB0_419
	v_max_f32_e32 v100, v100, v100
	v_max_f32_e32 v101, v131, v131
	v_max_f32_e32 v101, v101, v100
	v_sub_f32_e32 v100, v131, v101
	v_exp_f32_e32 v100, v100
	v_mov_b32_e32 v131, v101
	v_mul_f32_e32 v135, v135, v100
	v_mul_f32_e64 v30, v30, v100
	v_mul_f32_e64 v31, v31, v100
	v_mul_f32_e64 v28, v28, v100
	v_mul_f32_e64 v29, v29, v100
	v_mul_f32_e64 v34, v34, v100
	v_mul_f32_e64 v35, v35, v100
	v_mul_f32_e64 v32, v32, v100
	v_mul_f32_e64 v33, v33, v100
	v_mul_f32_e64 v38, v38, v100
	v_mul_f32_e64 v39, v39, v100
	v_mul_f32_e64 v36, v36, v100
	v_mul_f32_e64 v37, v37, v100
	v_mul_f32_e64 v26, v26, v100
	v_mul_f32_e64 v27, v27, v100
	v_mul_f32_e64 v24, v24, v100
	v_mul_f32_e64 v25, v25, v100
.LBB0_419:
	ds_read_b128 v[100:103], v165 offset:6656
	v_sub_f32_e32 v92, v92, v131
	v_exp_f32_e32 v169, v92
	v_sub_f32_e32 v92, v93, v131
	v_exp_f32_e32 v201, v92
	v_sub_f32_e32 v92, v94, v131
	v_exp_f32_e32 v202, v92
	v_sub_f32_e32 v92, v95, v131
	v_exp_f32_e32 v203, v92
	v_sub_f32_e32 v92, v96, v131
	v_exp_f32_e32 v204, v92
	v_sub_f32_e32 v92, v97, v131
	v_exp_f32_e32 v205, v92
	v_sub_f32_e32 v92, v98, v131
	v_exp_f32_e32 v206, v92
	v_sub_f32_e32 v92, v99, v131
	v_exp_f32_e32 v207, v92
	v_cvt_pk_bf16_f32 v92, v169, v201
	v_cvt_pk_bf16_f32 v93, v202, v203
	v_cvt_pk_bf16_f32 v94, v204, v205
	v_cvt_pk_bf16_f32 v95, v206, v207
	ds_read_b128 v[104:107], v165 offset:6720
	ds_read_b128 v[108:111], v165 offset:6784
	v_mfma_f32_16x16x32_bf16 v[24:27], v[76:79], v[92:95], v[24:27]
	ds_read_b128 v[112:115], v165 offset:9984
	ds_read_b128 v[96:99], v165 offset:10048
	s_waitcnt lgkmcnt(4)
	v_mfma_f32_16x16x32_bf16 v[76:79], v[100:103], v[20:23], 0
	v_mfma_f32_16x16x32_bf16 v[28:31], v[80:83], v[92:95], v[28:31]
	v_add_f32_e32 v80, 0, v116
	v_add_f32_e32 v80, v167, v80
	v_add_f32_e32 v80, v117, v80
	s_waitcnt lgkmcnt(3)
	v_mfma_f32_16x16x32_bf16 v[76:79], v[104:107], v[12:15], v[76:79]
	v_add_f32_e32 v80, v118, v80
	v_mfma_f32_16x16x32_bf16 v[32:35], v[84:87], v[92:95], v[32:35]
	v_mfma_f32_16x16x32_bf16 v[36:39], v[88:91], v[92:95], v[36:39]
	ds_read_b128 v[92:95], v165 offset:10112
	s_waitcnt lgkmcnt(3)
	v_mfma_f32_16x16x32_bf16 v[116:119], v[108:111], v[16:19], v[76:79]
	s_nop 2
	v_add_f32_e32 v76, v120, v80
	v_add_f32_e32 v80, v168, v76
	s_waitcnt lgkmcnt(2)
	v_mfma_f32_16x16x32_bf16 v[76:79], v[112:115], v[20:23], 0
	v_add_f32_e32 v80, v121, v80
	v_add_f32_e32 v80, v122, v80
	v_add_f32_e32 v139, v139, v80
	s_waitcnt lgkmcnt(1)
	v_mfma_f32_16x16x32_bf16 v[120:123], v[96:99], v[12:15], v[76:79]
	ds_read_b128 v[88:91], v166 offset:13376
	ds_read_b128 v[84:87], v166 offset:15680
	ds_read_b128 v[80:83], v166 offset:17984
	ds_read_b128 v[76:79], v166 offset:20288
	v_max_f32_e32 v165, v117, v117
	v_max_f32_e32 v166, v116, v116
	s_waitcnt lgkmcnt(4)
	v_mfma_f32_16x16x32_bf16 v[120:123], v[92:95], v[16:19], v[120:123]
	v_max_f32_e32 v165, v166, v165
	v_max_f32_e32 v166, v119, v119
	v_max_f32_e32 v167, v118, v118
	v_max_f32_e32 v166, v167, v166
	s_nop 3
	v_max_f32_e32 v167, v123, v123
	v_max_f32_e32 v168, v122, v122
	v_max_f32_e32 v167, v168, v167
	v_max3_f32 v167, v120, v121, v167
	v_max3_f32 v165, v165, v166, v167
	v_mov_b32_e32 v166, v165
	s_nop 1
	v_permlane16_swap_b32_e32 v165, v166
	v_max_f32_e32 v166, v166, v166
	v_max_f32_e32 v165, v165, v165
	v_max_f32_e32 v165, v165, v166
	v_mov_b32_e32 v166, v165
	s_nop 1
	v_permlane32_swap_b32_e32 v165, v166
	v_max_f32_e32 v166, v166, v166
	v_max_f32_e32 v165, v165, v165
	v_max_f32_e32 v165, v165, v166
	v_sub_f32_e32 v166, v165, v133
	v_cmp_lt_f32_e32 vcc, s4, v166
	s_cbranch_vccz .LBB0_421
	v_max_f32_e32 v165, v165, v165
	v_max_f32_e32 v166, v133, v133
	v_max_f32_e32 v165, v166, v165
	v_sub_f32_e32 v133, v133, v165
	v_exp_f32_e32 v166, v133
	v_mov_b32_e32 v133, v165
	v_mul_f32_e32 v139, v139, v166
	v_mul_f32_e64 v74, v74, v166
	v_mul_f32_e64 v75, v75, v166
	v_mul_f32_e64 v72, v72, v166
	v_mul_f32_e64 v73, v73, v166
	v_mul_f32_e64 v70, v70, v166
	v_mul_f32_e64 v71, v71, v166
	v_mul_f32_e64 v68, v68, v166
	v_mul_f32_e64 v69, v69, v166
	v_mul_f32_e64 v66, v66, v166
	v_mul_f32_e64 v67, v67, v166
	v_mul_f32_e64 v64, v64, v166
	v_mul_f32_e64 v65, v65, v166
	v_mul_f32_e64 v42, v42, v166
	v_mul_f32_e64 v43, v43, v166
	v_mul_f32_e64 v40, v40, v166
	v_mul_f32_e64 v41, v41, v166
.LBB0_421:
	v_mfma_f32_16x16x32_bf16 v[100:103], v[100:103], v[8:11], 0
	v_add_f32_e32 v165, 0, v169
	v_add_f32_e32 v165, v201, v165
	v_add_f32_e32 v165, v202, v165
	v_mfma_f32_16x16x32_bf16 v[100:103], v[104:107], v[4:7], v[100:103]
	v_add_f32_e32 v165, v203, v165
	v_add_f32_e32 v165, v204, v165
	v_sub_f32_e32 v116, v116, v133
	v_mfma_f32_16x16x32_bf16 v[104:107], v[112:115], v[8:11], 0
	v_sub_f32_e32 v117, v117, v133
	v_sub_f32_e32 v118, v118, v133
	v_sub_f32_e32 v119, v119, v133
	v_mfma_f32_16x16x32_bf16 v[96:99], v[96:99], v[4:7], v[104:107]
	v_sub_f32_e32 v120, v120, v133
	v_sub_f32_e32 v121, v121, v133
	v_sub_f32_e32 v122, v122, v133
	v_mfma_f32_16x16x32_bf16 v[100:103], v[108:111], v[0:3], v[100:103]
	v_sub_f32_e32 v123, v123, v133
	v_add_f32_e32 v165, v205, v165
	v_exp_f32_e32 v116, v116
	v_mfma_f32_16x16x32_bf16 v[92:95], v[92:95], v[0:3], v[96:99]
	v_exp_f32_e32 v117, v117
	v_exp_f32_e32 v118, v118
	v_exp_f32_e32 v119, v119
	s_nop 0
	v_max_f32_e32 v96, v101, v101
	v_max_f32_e32 v97, v100, v100
	v_max_f32_e32 v96, v97, v96
	v_max_f32_e32 v97, v103, v103
	v_max_f32_e32 v98, v102, v102
	v_max_f32_e32 v97, v98, v97
	v_max_f32_e32 v98, v95, v95
	v_max_f32_e32 v99, v94, v94
	v_max_f32_e32 v98, v99, v98
	v_max3_f32 v98, v92, v93, v98
	v_max3_f32 v96, v96, v97, v98
	v_mov_b32_e32 v97, v96
	s_nop 1
	v_permlane16_swap_b32_e32 v96, v97
	v_max_f32_e32 v97, v97, v97
	v_max_f32_e32 v96, v96, v96
	v_max_f32_e32 v96, v96, v97
	v_mov_b32_e32 v97, v96
	s_nop 1
	v_permlane32_swap_b32_e32 v96, v97
	v_exp_f32_e32 v120, v120
	v_exp_f32_e32 v121, v121
	v_exp_f32_e32 v122, v122
	v_exp_f32_e32 v123, v123
	v_cvt_pk_bf16_f32 v166, v116, v117
	v_cvt_pk_bf16_f32 v167, v118, v119
	v_cvt_pk_bf16_f32 v168, v120, v121
	v_cvt_pk_bf16_f32 v169, v122, v123
	v_max_f32_e32 v97, v97, v97
	s_waitcnt lgkmcnt(3)
	v_mfma_f32_16x16x32_bf16 v[72:75], v[88:91], v[166:169], v[72:75]
	v_max_f32_e32 v96, v96, v96
	v_add_f32_e32 v165, v206, v165
	v_max_f32_e32 v96, v96, v97
	s_waitcnt lgkmcnt(2)
	v_mfma_f32_16x16x32_bf16 v[68:71], v[84:87], v[166:169], v[68:71]
	v_add_f32_e32 v165, v207, v165
	v_sub_f32_e32 v97, v96, v131
	v_add_f32_e32 v135, v135, v165
	s_waitcnt lgkmcnt(1)
	v_mfma_f32_16x16x32_bf16 v[64:67], v[80:83], v[166:169], v[64:67]
	v_cmp_lt_f32_e32 vcc, s4, v97
	s_waitcnt lgkmcnt(0)
	v_mfma_f32_16x16x32_bf16 v[40:43], v[76:79], v[166:169], v[40:43]
	s_cbranch_vccz .LBB0_414
	v_max_f32_e32 v96, v96, v96
	v_max_f32_e32 v97, v131, v131
	v_max_f32_e32 v97, v97, v96
	v_sub_f32_e32 v96, v131, v97
	v_exp_f32_e32 v96, v96
	v_mov_b32_e32 v131, v97
	v_mul_f32_e32 v135, v135, v96
	v_mul_f32_e64 v30, v30, v96
	v_mul_f32_e64 v31, v31, v96
	v_mul_f32_e64 v28, v28, v96
	v_mul_f32_e64 v29, v29, v96
	v_mul_f32_e64 v34, v34, v96
	v_mul_f32_e64 v35, v35, v96
	v_mul_f32_e64 v32, v32, v96
	v_mul_f32_e64 v33, v33, v96
	v_mul_f32_e64 v38, v38, v96
	v_mul_f32_e64 v39, v39, v96
	v_mul_f32_e64 v36, v36, v96
	v_mul_f32_e64 v37, v37, v96
	v_mul_f32_e64 v26, v26, v96
	v_mul_f32_e64 v27, v27, v96
	v_mul_f32_e64 v24, v24, v96
	v_mul_f32_e64 v25, v25, v96
	s_branch .LBB0_414
.LBB0_423:
	v_add_u32_e32 v105, v128, v163
	ds_read_b128 v[84:87], v105 offset:22528
	ds_read_b128 v[88:91], v105 offset:22592
	ds_read_b128 v[92:95], v105 offset:22656
	ds_read_b128 v[96:99], v105 offset:25856
	ds_read_b128 v[80:83], v105 offset:25920
	ds_read_b128 v[76:79], v105 offset:25984
	s_waitcnt lgkmcnt(5)
	v_mfma_f32_16x16x32_bf16 v[60:63], v[84:87], v[20:23], 0
	v_add_u32_e32 v104, v128, v162
	ds_read_b128 v[48:51], v104 offset:35840
	ds_read_b128 v[52:55], v104 offset:38144
	ds_read_b128 v[56:59], v104 offset:40448
	ds_read_b128 v[44:47], v104 offset:42752
	s_waitcnt lgkmcnt(6)
	v_mfma_f32_16x16x32_bf16 v[100:103], v[96:99], v[20:23], 0
	v_mfma_f32_16x16x32_bf16 v[60:63], v[88:91], v[12:15], v[60:63]
	s_waitcnt lgkmcnt(5)
	v_mfma_f32_16x16x32_bf16 v[100:103], v[80:83], v[12:15], v[100:103]
	v_mfma_f32_16x16x32_bf16 v[60:63], v[92:95], v[16:19], v[60:63]
	s_waitcnt lgkmcnt(4)
	v_mfma_f32_16x16x32_bf16 v[100:103], v[76:79], v[16:19], v[100:103]
	s_nop 5
	v_max_f32_e32 v106, v61, v61
	v_max_f32_e32 v107, v60, v60
	v_max_f32_e32 v106, v107, v106
	v_max_f32_e32 v107, v63, v63
	v_max_f32_e32 v108, v62, v62
	v_max_f32_e32 v107, v108, v107
	v_max_f32_e32 v108, v103, v103
	v_max_f32_e32 v109, v102, v102
	v_max_f32_e32 v108, v109, v108
	v_max3_f32 v108, v100, v101, v108
	v_max3_f32 v106, v106, v107, v108
	v_mov_b32_e32 v107, v106
	s_nop 1
	v_permlane16_swap_b32_e32 v106, v107
	v_max_f32_e32 v107, v107, v107
	v_max_f32_e32 v106, v106, v106
	v_max_f32_e32 v106, v106, v107
	v_mov_b32_e32 v107, v106
	s_nop 1
	v_permlane32_swap_b32_e32 v106, v107
	v_max_f32_e32 v107, v107, v107
	v_max_f32_e32 v106, v106, v106
	v_max_f32_e32 v106, v106, v107
	v_sub_f32_e32 v107, v106, v133
	v_cmp_lt_f32_e32 vcc, s4, v107
	s_cbranch_vccz .LBB0_425
	v_max_f32_e32 v106, v106, v106
	v_max_f32_e32 v107, v133, v133
	v_max_f32_e32 v107, v107, v106
	v_sub_f32_e32 v106, v133, v107
	v_exp_f32_e32 v106, v106
	v_mov_b32_e32 v133, v107
	v_mul_f32_e32 v139, v139, v106
	v_mul_f32_e64 v74, v74, v106
	v_mul_f32_e64 v75, v75, v106
	v_mul_f32_e64 v72, v72, v106
	v_mul_f32_e64 v73, v73, v106
	v_mul_f32_e64 v70, v70, v106
	v_mul_f32_e64 v71, v71, v106
	v_mul_f32_e64 v68, v68, v106
	v_mul_f32_e64 v69, v69, v106
	v_mul_f32_e64 v66, v66, v106
	v_mul_f32_e64 v67, v67, v106
	v_mul_f32_e64 v64, v64, v106
	v_mul_f32_e64 v65, v65, v106
	v_mul_f32_e64 v42, v42, v106
	v_mul_f32_e64 v43, v43, v106
	v_mul_f32_e64 v40, v40, v106
	v_mul_f32_e64 v41, v41, v106
.LBB0_425:
	v_sub_f32_e32 v60, v60, v133
	v_exp_f32_e32 v106, v60
	v_sub_f32_e32 v60, v61, v133
	v_exp_f32_e32 v108, v60
	v_sub_f32_e32 v60, v62, v133
	v_exp_f32_e32 v107, v60
	v_sub_f32_e32 v60, v63, v133
	v_exp_f32_e32 v109, v60
	v_sub_f32_e32 v60, v100, v133
	v_exp_f32_e32 v100, v60
	v_sub_f32_e32 v60, v101, v133
	v_exp_f32_e32 v110, v60
	v_sub_f32_e32 v60, v102, v133
	v_exp_f32_e32 v101, v60
	v_sub_f32_e32 v60, v103, v133
	v_exp_f32_e32 v102, v60
	v_cvt_pk_bf16_f32 v112, v106, v108
	v_cvt_pk_bf16_f32 v113, v107, v109
	v_cvt_pk_bf16_f32 v114, v100, v110
	v_cvt_pk_bf16_f32 v115, v101, v102
	s_waitcnt lgkmcnt(1)
	v_mfma_f32_16x16x32_bf16 v[60:63], v[56:59], v[112:115], v[64:67]
	v_mfma_f32_16x16x32_bf16 v[64:67], v[84:87], v[8:11], 0
	v_mfma_f32_16x16x32_bf16 v[64:67], v[88:91], v[4:7], v[64:67]
	v_mfma_f32_16x16x32_bf16 v[84:87], v[92:95], v[0:3], v[64:67]
	v_mfma_f32_16x16x32_bf16 v[64:67], v[96:99], v[8:11], 0
	v_mfma_f32_16x16x32_bf16 v[64:67], v[80:83], v[4:7], v[64:67]
	s_nop 5
	v_max_f32_e32 v80, v87, v87
	v_max_f32_e32 v81, v86, v86
	v_max_f32_e32 v88, v85, v85
	v_mfma_f32_16x16x32_bf16 v[76:79], v[76:79], v[0:3], v[64:67]
	v_max_f32_e32 v89, v84, v84
	v_max_f32_e32 v80, v81, v80
	v_max_f32_e32 v88, v89, v88
	v_mfma_f32_16x16x32_bf16 v[72:75], v[48:51], v[112:115], v[72:75]
	v_mfma_f32_16x16x32_bf16 v[68:71], v[52:55], v[112:115], v[68:71]
	s_nop 2
	v_max_f32_e32 v64, v79, v79
	v_max_f32_e32 v65, v78, v78
	v_max_f32_e32 v81, v65, v64
	s_waitcnt lgkmcnt(0)
	v_mfma_f32_16x16x32_bf16 v[64:67], v[44:47], v[112:115], v[40:43]
	s_nop 2
	v_max3_f32 v40, v76, v77, v81
	v_max3_f32 v40, v88, v80, v40
	v_mov_b32_e32 v41, v40
	s_nop 1
	v_permlane16_swap_b32_e32 v40, v41
	v_max_f32_e32 v41, v41, v41
	v_max_f32_e32 v40, v40, v40
	v_max_f32_e32 v40, v40, v41
	v_mov_b32_e32 v41, v40
	s_nop 1
	v_permlane32_swap_b32_e32 v40, v41
	v_max_f32_e32 v41, v41, v41
	v_max_f32_e32 v40, v40, v40
	v_max_f32_e32 v40, v40, v41
	v_sub_f32_e32 v41, v40, v131
	v_cmp_lt_f32_e32 vcc, s4, v41
	s_cbranch_vccz .LBB0_427
	v_max_f32_e32 v40, v40, v40
	v_max_f32_e32 v41, v131, v131
	v_max_f32_e32 v41, v41, v40
	v_sub_f32_e32 v40, v131, v41
	v_exp_f32_e32 v40, v40
	v_mov_b32_e32 v131, v41
	v_mul_f32_e32 v135, v135, v40
	v_mul_f32_e64 v30, v30, v40
	v_mul_f32_e64 v31, v31, v40
	v_mul_f32_e64 v28, v28, v40
	v_mul_f32_e64 v29, v29, v40
	v_mul_f32_e64 v34, v34, v40
	v_mul_f32_e64 v35, v35, v40
	v_mul_f32_e64 v32, v32, v40
	v_mul_f32_e64 v33, v33, v40
	v_mul_f32_e64 v38, v38, v40
	v_mul_f32_e64 v39, v39, v40
	v_mul_f32_e64 v36, v36, v40
	v_mul_f32_e64 v37, v37, v40
	v_mul_f32_e64 v26, v26, v40
	v_mul_f32_e64 v27, v27, v40
	v_mul_f32_e64 v24, v24, v40
	v_mul_f32_e64 v25, v25, v40
.LBB0_427:
	v_sub_f32_e32 v40, v84, v131
	v_exp_f32_e32 v103, v40
	v_sub_f32_e32 v40, v85, v131
	v_exp_f32_e32 v111, v40
	v_sub_f32_e32 v40, v86, v131
	v_exp_f32_e32 v112, v40
	v_sub_f32_e32 v40, v87, v131
	ds_read_b128 v[84:87], v105 offset:29184
	ds_read_b128 v[88:91], v105 offset:29248
	ds_read_b128 v[92:95], v105 offset:29312
	ds_read_b128 v[96:99], v105 offset:32512
	ds_read_b128 v[80:83], v105 offset:32576
	v_exp_f32_e32 v113, v40
	v_sub_f32_e32 v40, v76, v131
	v_exp_f32_e32 v114, v40
	v_sub_f32_e32 v40, v77, v131
	v_exp_f32_e32 v115, v40
	v_sub_f32_e32 v40, v78, v131
	v_exp_f32_e32 v116, v40
	v_sub_f32_e32 v40, v79, v131
	v_exp_f32_e32 v117, v40
	v_cvt_pk_bf16_f32 v76, v103, v111
	v_cvt_pk_bf16_f32 v77, v112, v113
	v_cvt_pk_bf16_f32 v78, v114, v115
	v_cvt_pk_bf16_f32 v79, v116, v117
	s_nop 0
	v_mfma_f32_16x16x32_bf16 v[40:43], v[48:51], v[76:79], v[28:31]
	v_mfma_f32_16x16x32_bf16 v[28:31], v[56:59], v[76:79], v[36:39]
	s_waitcnt lgkmcnt(4)
	v_mfma_f32_16x16x32_bf16 v[36:39], v[84:87], v[20:23], 0
	v_mfma_f32_16x16x32_bf16 v[32:35], v[52:55], v[76:79], v[32:35]
	v_mfma_f32_16x16x32_bf16 v[24:27], v[44:47], v[76:79], v[24:27]
	ds_read_b128 v[76:79], v105 offset:32640
	v_add_f32_e32 v44, 0, v106
	v_add_f32_e32 v44, v108, v44
	s_waitcnt lgkmcnt(2)
	v_mfma_f32_16x16x32_bf16 v[20:23], v[96:99], v[20:23], 0
	v_add_f32_e32 v44, v107, v44
	v_add_f32_e32 v44, v109, v44
	v_mfma_f32_16x16x32_bf16 v[36:39], v[88:91], v[12:15], v[36:39]
	s_waitcnt lgkmcnt(1)
	v_mfma_f32_16x16x32_bf16 v[52:55], v[80:83], v[12:15], v[20:23]
	v_mfma_f32_16x16x32_bf16 v[48:51], v[92:95], v[16:19], v[36:39]
	s_waitcnt lgkmcnt(0)
	v_mfma_f32_16x16x32_bf16 v[16:19], v[76:79], v[16:19], v[52:55]
	s_nop 2
	v_add_f32_e32 v36, v100, v44
	v_add_f32_e32 v36, v110, v36
	v_add_f32_e32 v36, v101, v36
	v_max_f32_e32 v52, v49, v49
	v_max_f32_e32 v53, v48, v48
	v_max_f32_e32 v52, v53, v52
	v_max_f32_e32 v53, v51, v51
	v_max_f32_e32 v54, v50, v50
	v_max_f32_e32 v53, v54, v53
	v_max_f32_e32 v54, v19, v19
	v_max_f32_e32 v55, v18, v18
	v_max_f32_e32 v54, v55, v54
	v_max3_f32 v54, v16, v17, v54
	v_max3_f32 v52, v52, v53, v54
	v_mov_b32_e32 v53, v52
	s_nop 1
	v_permlane16_swap_b32_e32 v52, v53
	v_add_f32_e32 v36, v102, v36
	v_max_f32_e32 v53, v53, v53
	v_max_f32_e32 v52, v52, v52
	v_add_f32_e32 v100, v139, v36
	ds_read_b128 v[12:15], v104 offset:35904
	ds_read_b128 v[20:23], v104 offset:38208
	ds_read_b128 v[36:39], v104 offset:40512
	ds_read_b128 v[44:47], v104 offset:42816
	v_max_f32_e32 v52, v52, v53
	v_mov_b32_e32 v53, v52
	s_nop 1
	v_permlane32_swap_b32_e32 v52, v53
	v_max_f32_e32 v53, v53, v53
	v_max_f32_e32 v52, v52, v52
	v_max_f32_e32 v52, v52, v53
	v_sub_f32_e32 v53, v52, v133
	v_cmp_lt_f32_e32 vcc, s4, v53
	s_cbranch_vccz .LBB0_429
	v_max_f32_e32 v52, v52, v52
	v_max_f32_e32 v53, v133, v133
	v_max_f32_e32 v53, v53, v52
	v_sub_f32_e32 v52, v133, v53
	v_exp_f32_e32 v52, v52
	v_mov_b32_e32 v133, v53
	v_mul_f32_e32 v100, v100, v52
	v_mul_f32_e64 v74, v74, v52
	v_mul_f32_e64 v75, v75, v52
	v_mul_f32_e64 v72, v72, v52
	v_mul_f32_e64 v73, v73, v52
	v_mul_f32_e64 v70, v70, v52
	v_mul_f32_e64 v71, v71, v52
	v_mul_f32_e64 v68, v68, v52
	v_mul_f32_e64 v69, v69, v52
	v_mul_f32_e64 v62, v62, v52
	v_mul_f32_e64 v63, v63, v52
	v_mul_f32_e64 v60, v60, v52
	v_mul_f32_e64 v61, v61, v52
	v_mul_f32_e64 v66, v66, v52
	v_mul_f32_e64 v67, v67, v52
	v_mul_f32_e64 v64, v64, v52
	v_mul_f32_e64 v65, v65, v52
.LBB0_429:
	v_sub_f32_e32 v48, v48, v133
	v_sub_f32_e32 v16, v16, v133
	v_exp_f32_e32 v102, v48
	v_sub_f32_e32 v48, v49, v133
	v_exp_f32_e32 v106, v16
	v_sub_f32_e32 v16, v17, v133
	v_add_f32_e32 v52, 0, v103
	v_exp_f32_e32 v103, v48
	v_sub_f32_e32 v48, v50, v133
	v_exp_f32_e32 v107, v16
	v_sub_f32_e32 v16, v18, v133
	v_exp_f32_e32 v104, v48
	v_sub_f32_e32 v48, v51, v133
	v_exp_f32_e32 v108, v16
	v_sub_f32_e32 v16, v19, v133
	v_exp_f32_e32 v105, v48
	v_exp_f32_e32 v109, v16
	v_cvt_pk_bf16_f32 v16, v102, v103
	v_cvt_pk_bf16_f32 v17, v104, v105
	v_cvt_pk_bf16_f32 v18, v106, v107
	v_cvt_pk_bf16_f32 v19, v108, v109
	v_add_f32_e32 v52, v111, v52
	s_waitcnt lgkmcnt(1)
	v_mfma_f32_16x16x32_bf16 v[48:51], v[36:39], v[16:19], v[60:63]
	v_add_f32_e32 v52, v112, v52
	v_add_f32_e32 v52, v113, v52
	v_add_f32_e32 v52, v114, v52
	v_mfma_f32_16x16x32_bf16 v[60:63], v[84:87], v[8:11], 0
	v_add_f32_e32 v52, v115, v52
	v_add_f32_e32 v52, v116, v52
	v_add_f32_e32 v52, v117, v52
	v_mfma_f32_16x16x32_bf16 v[8:11], v[96:99], v[8:11], 0
	v_add_f32_e32 v101, v135, v52
	v_mfma_f32_16x16x32_bf16 v[60:63], v[88:91], v[4:7], v[60:63]
	v_mfma_f32_16x16x32_bf16 v[4:7], v[80:83], v[4:7], v[8:11]
	v_mfma_f32_16x16x32_bf16 v[60:63], v[92:95], v[0:3], v[60:63]
	v_mfma_f32_16x16x32_bf16 v[0:3], v[76:79], v[0:3], v[4:7]
	v_mfma_f32_16x16x32_bf16 v[56:59], v[12:15], v[16:19], v[72:75]
	s_nop 5
	v_max_f32_e32 v4, v61, v61
	v_max_f32_e32 v5, v60, v60
	v_max_f32_e32 v4, v5, v4
	v_max_f32_e32 v5, v63, v63
	v_max_f32_e32 v6, v62, v62
	v_max_f32_e32 v5, v6, v5
	v_max_f32_e32 v6, v3, v3
	v_max_f32_e32 v7, v2, v2
	v_max_f32_e32 v6, v7, v6
	v_max3_f32 v6, v0, v1, v6
	v_max3_f32 v4, v4, v5, v6
	v_mov_b32_e32 v5, v4
	s_nop 1
	v_permlane16_swap_b32_e32 v4, v5
	v_max_f32_e32 v5, v5, v5
	v_max_f32_e32 v4, v4, v4
	v_max_f32_e32 v4, v4, v5
	v_mov_b32_e32 v5, v4
	s_nop 1
	v_permlane32_swap_b32_e32 v4, v5
	v_mfma_f32_16x16x32_bf16 v[52:55], v[20:23], v[16:19], v[68:71]
	v_max_f32_e32 v5, v5, v5
	v_max_f32_e32 v4, v4, v4
	v_max_f32_e32 v4, v4, v5
	s_waitcnt lgkmcnt(0)
	v_mfma_f32_16x16x32_bf16 v[16:19], v[44:47], v[16:19], v[64:67]
	v_sub_f32_e32 v5, v4, v131
	v_cmp_lt_f32_e32 vcc, s4, v5
	s_cbranch_vccz .LBB0_431
	v_max_f32_e32 v4, v4, v4
	v_max_f32_e32 v5, v131, v131
	v_max_f32_e32 v5, v5, v4
	v_sub_f32_e32 v4, v131, v5
	v_exp_f32_e32 v4, v4
	v_mov_b32_e32 v131, v5
	v_mul_f32_e32 v101, v101, v4
	v_mul_f32_e64 v42, v42, v4
	v_mul_f32_e64 v43, v43, v4
	v_mul_f32_e64 v40, v40, v4
	v_mul_f32_e64 v41, v41, v4
	v_mul_f32_e64 v34, v34, v4
	v_mul_f32_e64 v35, v35, v4
	v_mul_f32_e64 v32, v32, v4
	v_mul_f32_e64 v33, v33, v4
	v_mul_f32_e64 v30, v30, v4
	v_mul_f32_e64 v31, v31, v4
	v_mul_f32_e64 v28, v28, v4
	v_mul_f32_e64 v29, v29, v4
	v_mul_f32_e64 v26, v26, v4
	v_mul_f32_e64 v27, v27, v4
	v_mul_f32_e64 v24, v24, v4
	v_mul_f32_e64 v25, v25, v4
